# G3 start de-phasing retuned to 0/4/8/12 us (seam after G3 is XCD-local)
# speedup vs baseline: 1.0023x; 1.0023x over previous
.LBB0_366:
	s_cmp_lt_i32 s56, 5
	s_cselect_b64 s[0:1], -1, 0
	s_and_b64 s[8:9], s[0:1], s[4:5]
	s_andn2_b64 vcc, exec, s[8:9]
	s_cbranch_vccnz .LBB0_408
	s_bfe_u32 s0, s2, 0x20003
	s_cmp_eq_u32 s0, 0
	v_mbcnt_lo_u32_b32 v0, -1, 0
	v_mbcnt_hi_u32_b32 v0, -1, v0
	s_cbranch_scc1 .LBB0_370
	s_mul_i32 s0, s0, 2
